# MIX fp8 conversion: class members take adjacent items (perm start) + counted waits leave prev item's 4 stores in flight (vmcnt 20)
# baseline (speedup 1.0000x reference)
; __device__ __forceinline__ void phase_prep(const Frame& F, int l) {
;     if (FAST_RET && FAST_NSA) {
;         const int first = F.G > 32 ? 16 : 0;
;         if (F.bid < first || first == 0) {
;             for (int u = F.bid; u < 16; u += F.G) { const int which = u >> 3, p0 = (u & 7) * 2, lw = l * 2 + which;
;                 RowCmp R{p0}; EpiCmp E{F.lds, (unsigned char*)F.ws, (const float*)(F.ws + WS_CB1) + lw * 128, (const bf16*)(F.ws + WS_CW2T) + (size_t)lw * 64 * 128, which, p0, F.wave};
;                 gemm_unit(F, (const bf16*)(F.ws + (which ? WS_NVC : WS_NKC)), R, (const bf16*)(F.ws + WS_CW1T) + (size_t)lw * 128 * 2048, E, 64, 2048); }
;             __syncthreads();
;         }
;         if (F.bid >= first) {
;             conv_tokens(F, l, first); for (int u = F.bid - first; u < NB * 4 * 16; u += F.G - first) ret_kv_unit(F, u); __syncthreads();
;             gates_tiles(F, l, first);
;             fp8_convert_range(F, l, F.bid - first, F.G - first, CONV_SPLIT);
;         }
; __device__ __forceinline__ void phase_mix(const Frame& F, int l) {
;     ...
;     if (FAST_RET && FAST_NSA) {
;         const int cls = F.bid % 3;
;         if (cls == 0) fp8_convert_range(F, l, CONV_SPLIT + F.bid, F.G, CONV_ITEMS);
;         for (int u = F.bid; u < NB * 4 * 16; u += F.G) ret_out_unit(F, l, u);
;         __syncthreads();
;         if (cls == 1) fp8_convert_range(F, l, CONV_SPLIT + F.bid, F.G, CONV_ITEMS);
;         for (int p = F.bid; p < 512; p += F.G) { const int plane = (p & 255) >> 4, pi = p & 15; nsa_unit(launder(F), plane, p < 256 ? pi : 31 - pi); }
;         if (cls == 2) fp8_convert_range(F, l, CONV_SPLIT + F.bid, F.G, CONV_ITEMS);
.LBB0_532:
	s_cmpk_lt_i32 s80, 0x300
	s_cselect_b64 s[4:5], -1, 0
	s_ashr_i32 s3, s80, 31
	s_lshr_b32 s3, s3, 29
	s_add_i32 s3, s80, s3
	s_ashr_i32 s12, s3, 3
	s_and_b32 s3, s3, -8
	s_sub_i32 s13, s80, s3
	v_writelane_b32 v251, s4, 10
	s_lshl_b32 s3, s13, 5
	s_cmp_lt_i32 s13, 0
	v_writelane_b32 v251, s5, 11
	s_movk_i32 s4, 0x61
	s_cselect_b32 s4, s4, 0x60
	s_mul_i32 s4, s4, s13
	s_mul_i32 s5, s13, 33
	s_cselect_b32 s3, s5, s3
	s_add_i32 s4, s4, s12
	s_mul_hi_i32 s5, s4, 0x2aaaaaab
	s_lshr_b32 s6, s5, 31
	s_ashr_i32 s5, s5, 4
	s_add_i32 s5, s5, s6
	s_mul_i32 s6, s5, 0x60
	s_sub_i32 s6, s4, s6
	s_bfe_i32 s4, s6, 0x80000
	s_bfe_u32 s4, s4, 0x3000c
	s_add_i32 s7, s6, s4
	s_bfe_i32 s4, s7, 0x80000
	s_and_b32 s7, s7, 0xf8
	s_sub_i32 s6, s6, s7
	s_lshl_b32 s5, s5, 3
	s_sext_i32_i16 s8, s4
	s_sext_i32_i8 s6, s6
	s_add_i32 s14, s5, s6
	s_ashr_i32 s5, s8, 3
	v_writelane_b32 v251, s5, 12
	s_lshr_b32 s4, s8, 3
	v_readlane_b32 s8, v251, 0
	v_readlane_b32 s10, v251, 2
	v_readlane_b32 s11, v251, 3
	s_add_u32 s6, s10, 0x4200
	s_addc_u32 s7, s11, 0
	s_add_u32 s28, s10, 0x4400
	v_readlane_b32 s9, v251, 1
	v_writelane_b32 v251, s6, 13
	s_addc_u32 s29, s11, 0
	s_load_dwordx8 s[16:23], s[0:1], 0x78
	v_writelane_b32 v251, s7, 14
	s_add_u32 s6, s10, 0x4500
	s_addc_u32 s7, s11, 0
	v_writelane_b32 v251, s6, 15
	s_mov_b32 s35, 0
	v_mbcnt_lo_u32_b32 v1, -1, 0
	v_writelane_b32 v251, s7, 16
	s_add_u32 s6, s10, 0x4600
	s_addc_u32 s7, s11, 0
	v_writelane_b32 v251, s6, 17
	s_movk_i32 s70, 0x2000
	s_mov_b32 s71, 0x10000
	v_writelane_b32 v251, s7, 18
	s_add_u32 s6, s10, 0x4700
	s_addc_u32 s7, s11, 0
	v_writelane_b32 v251, s6, 19
	v_mov_b32_e32 v199, 0
	s_mov_b64 s[38:39], 0x100
	v_writelane_b32 v251, s7, 20
	s_add_u32 s6, s10, 0x4800
	s_addc_u32 s7, s11, 0
	v_writelane_b32 v251, s6, 21
	v_mov_b32_e32 v222, 1
	s_movk_i32 s77, 0x1000
	v_writelane_b32 v251, s7, 22
	s_add_u32 s6, s10, 0x4900
	s_addc_u32 s7, s11, 0
	v_writelane_b32 v251, s6, 23
	v_mov_b32_e32 v223, 0x3ca908c9
	s_brev_b32 s82, -2
	v_writelane_b32 v251, s7, 24
	s_add_u32 s6, s10, 0x4a00
	s_addc_u32 s7, s11, 0
	v_writelane_b32 v251, s6, 25
	s_mov_b32 s83, 0xbfb8aa3b
	s_mov_b32 s92, 0x42ce8ed0
	v_writelane_b32 v251, s7, 26
	s_add_u32 s6, s10, 0x4b00
	s_addc_u32 s7, s11, 0
	v_writelane_b32 v251, s6, 27
	s_mov_b32 s93, 0xc2b17218
	v_mov_b32_e32 v224, 0x2000
	v_writelane_b32 v251, s7, 28
	s_add_u32 s6, s10, 0x4c00
	s_addc_u32 s7, s11, 0
	v_writelane_b32 v251, s6, 29
	s_mov_b64 s[24:25], 0x4000
	v_mbcnt_hi_u32_b32 v225, -1, v1
	v_writelane_b32 v251, s7, 30
	s_add_u32 s6, s10, 0x4d00
	s_addc_u32 s7, s11, 0
	v_writelane_b32 v251, s6, 31
	v_mov_b32_e32 v226, 0x3727c5ac
	v_mov_b32_e32 v227, 0x260
	v_writelane_b32 v251, s7, 32
	s_add_u32 s6, s10, 0x4e00
	s_addc_u32 s7, s11, 0
	v_writelane_b32 v251, s6, 33
	s_mov_b64 s[94:95], 0x11000000
	v_mov_b32_e32 v228, 0x7f7f7f7f
	v_writelane_b32 v251, s7, 34
	s_add_u32 s6, s10, 0x4f00
	s_addc_u32 s7, s11, 0
	v_writelane_b32 v251, s6, 35
	v_mov_b32_e32 v229, 0x6f
	v_mov_b32_e32 v230, 0x7f800000
	v_writelane_b32 v251, s7, 36
	s_add_u32 s6, s10, 0x5000
	s_addc_u32 s7, s11, 0
	v_writelane_b32 v251, s6, 37
	v_mov_b32_e32 v231, 0x600
	v_mov_b32_e32 v232, 0x42000000
	v_writelane_b32 v251, s7, 38
	s_add_u32 s6, s10, 0x5100
	s_addc_u32 s7, s11, 0
	v_writelane_b32 v251, s6, 39
	v_mov_b32_e32 v233, 0x42800000
	v_mov_b32_e32 v234, 0xf149f2ca
	v_writelane_b32 v251, s7, 40
	s_add_u32 s6, s10, 0x5200
	s_addc_u32 s7, s11, 0
	v_writelane_b32 v251, s6, 41
	v_mov_b32_e32 v235, 0xce6e6b28
	v_mov_b32_e32 v236, 0x4e6e6b28
	v_writelane_b32 v251, s7, 42
	s_add_u32 s6, s10, 0x5300
	s_addc_u32 s7, s11, 0
	v_writelane_b32 v251, s6, 43
	s_cmp_eq_u32 s2, 15
	v_mov_b32_e32 v237, 0xff800000
	v_writelane_b32 v251, s7, 44
	s_cselect_b64 s[6:7], -1, 0
	v_writelane_b32 v251, s6, 45
	s_cmp_eq_u32 s2, 14
	v_mov_b32_e32 v238, 0x40e00000
	v_writelane_b32 v251, s7, 46
	s_cselect_b64 s[6:7], -1, 0
	v_writelane_b32 v251, s6, 47
	s_cmp_eq_u32 s2, 13
	s_mov_b32 s96, s35
	v_writelane_b32 v251, s7, 48
	s_cselect_b64 s[6:7], -1, 0
	v_writelane_b32 v251, s6, 49
	s_cmp_eq_u32 s2, 12
	s_nop 0
	v_writelane_b32 v251, s7, 50
	s_cselect_b64 s[6:7], -1, 0
	v_writelane_b32 v251, s6, 51
	s_cmp_eq_u32 s2, 11
	s_nop 0
	v_writelane_b32 v251, s7, 52
	s_cselect_b64 s[6:7], -1, 0
	v_writelane_b32 v251, s6, 53
	s_cmp_eq_u32 s2, 10
	s_nop 0
	v_writelane_b32 v251, s7, 54
	s_cselect_b64 s[6:7], -1, 0
	v_writelane_b32 v251, s6, 55
	s_cmp_eq_u32 s2, 9
	s_nop 0
	v_writelane_b32 v251, s7, 56
	s_cselect_b64 s[6:7], -1, 0
	v_writelane_b32 v251, s6, 57
	s_cmp_eq_u32 s2, 8
	s_nop 0
	v_writelane_b32 v251, s7, 58
	s_cselect_b64 s[6:7], -1, 0
	v_writelane_b32 v251, s6, 59
	s_cmp_eq_u32 s2, 7
	s_nop 0
	v_writelane_b32 v251, s7, 60
	s_cselect_b64 s[6:7], -1, 0
	v_writelane_b32 v251, s6, 61
	s_cmp_eq_u32 s2, 6
	s_nop 0
	v_writelane_b32 v251, s7, 62
	s_cselect_b64 s[6:7], -1, 0
	v_writelane_b32 v251, s6, 63
	s_cmp_eq_u32 s2, 5
	s_nop 0
	v_writelane_b32 v250, s7, 0
	s_cselect_b64 s[6:7], -1, 0
	v_writelane_b32 v250, s6, 1
	s_cmp_eq_u32 s2, 4
	s_nop 0
	v_writelane_b32 v250, s7, 2
	s_cselect_b64 s[6:7], -1, 0
	v_writelane_b32 v250, s6, 3
	s_cmp_eq_u32 s2, 3
	s_nop 0
	v_writelane_b32 v250, s7, 4
	s_cselect_b64 s[6:7], -1, 0
	v_writelane_b32 v250, s6, 5
	s_cmp_eq_u32 s2, 2
	s_nop 0
	v_writelane_b32 v250, s7, 6
	s_cselect_b64 s[6:7], -1, 0
	v_writelane_b32 v250, s6, 7
	s_cmp_eq_u32 s2, 1
	s_nop 0
	v_writelane_b32 v250, s7, 8
	s_cselect_b64 s[6:7], -1, 0
	v_writelane_b32 v250, s6, 9
	s_cmp_eq_u32 s2, 0
	s_nop 0
	v_writelane_b32 v250, s7, 10
	s_cselect_b64 s[6:7], -1, 0
	s_lshl_b32 s2, s2, 8
	s_add_u32 s2, s10, s2
	v_writelane_b32 v250, s6, 11
	s_addc_u32 s5, s11, 0
; __device__ __forceinline__ float w_qscale(float wmax) { return exp2f(floorf(log2f(128.f / fmaxf(wmax, 1e-30f)))); }
; __device__ __forceinline__ bool witem_decode(const Frame& F, int l, int it, WItem& t) {
;     constexpr int I_GU = 4 * 16, I_DN = 4 * 8, N_GU = NE * I_GU, N_DN = NE * I_DN;
;     const float* wmax = (const float*)((const unsigned*)(F.ws + WS_CTL) + CW_WMAX);
;     int r = it, nblk, item;
;     if (r < N_GU) { const int le = l * NE + r / I_GU; t.W = F.in[16] + (size_t)le * D * 2048; t.WT = (unsigned char*)(F.ws + WS_WGU) + (size_t)le * 2048 * D; t.N = 2048; t.map = 1; nblk = 16; item = r % I_GU; t.scale = w_qscale(wmax[l * 2 + 0]); }
;     else if ((r -= N_GU) < N_DN) { const int le = l * NE + r / I_DN; t.W = F.in[18] + (size_t)le * FF * D; t.WT = (unsigned char*)(F.ws + WS_WDN) + (size_t)le * D * FF; t.N = D; t.map = 3; nblk = 8; item = r % I_DN; t.scale = w_qscale(wmax[l * 2 + 1]); }
;     else return false;
;     t.k0 = 256 * (item / nblk); t.n0 = 128 * (item % nblk); return true;
; __device__ __forceinline__ void phase_mix(const Frame& F, int l) {
;     ...
;     if (FAST_RET && FAST_NSA) {
;         const int cls = F.bid % 3;
;         if (cls == 0) fp8_convert_range(F, l, CONV_SPLIT + F.bid, F.G, CONV_ITEMS);
;         for (int u = F.bid; u < NB * 4 * 16; u += F.G) ret_out_unit(F, l, u);
;         __syncthreads();
;         if (cls == 1) fp8_convert_range(F, l, CONV_SPLIT + F.bid, F.G, CONV_ITEMS);
;         for (int p = F.bid; p < 512; p += F.G) { const int plane = (p & 255) >> 4, pi = p & 15; nsa_unit(launder(F), plane, p < 256 ? pi : 31 - pi); }
;         if (cls == 2) fp8_convert_range(F, l, CONV_SPLIT + F.bid, F.G, CONV_ITEMS);
	s_nop 0
	v_writelane_b32 v250, s7, 12
	s_add_u32 s6, s2, 0x5400
	s_addc_u32 s7, s5, 0
	v_writelane_b32 v250, s6, 13
	s_nop 1
	v_writelane_b32 v250, s7, 14
	s_add_u32 s6, s2, 0x6400
	s_addc_u32 s7, s5, 0
	v_writelane_b32 v250, s6, 15
	s_nop 1
	v_writelane_b32 v250, s7, 16
	s_add_u32 s6, s10, 0x7400
	s_addc_u32 s7, s11, 0
	v_writelane_b32 v250, s6, 17
	s_nop 1
	v_writelane_b32 v250, s7, 18
	s_add_u32 s6, s10, 0x7500
	s_addc_u32 s7, s11, 0
	v_writelane_b32 v250, s6, 19
	s_cmp_lt_i32 s81, 33
	s_nop 0
	v_writelane_b32 v250, s7, 20
	s_cselect_b64 s[6:7], -1, 0
	s_and_b64 s[8:9], s[6:7], exec
	s_cselect_b32 s10, 0, 16
	s_cselect_b32 s2, 0, -16
	s_cmp_ge_i32 s80, s10
	s_cselect_b64 s[8:9], -1, 0
	v_writelane_b32 v250, s8, 21
	s_cmp_lt_i32 s80, s10
	s_nop 0
	v_writelane_b32 v250, s9, 22
	s_cselect_b64 s[8:9], -1, 0
	s_or_b64 s[6:7], s[6:7], s[8:9]
	v_writelane_b32 v250, s6, 23
	s_cmp_lt_i32 s80, 16
	s_nop 0
	v_writelane_b32 v250, s7, 24
	s_cselect_b64 s[6:7], -1, 0
	v_writelane_b32 v250, s6, 25
	s_sub_i32 s5, s80, s10
	s_sub_i32 s74, s81, s10
	v_writelane_b32 v250, s7, 26
	s_lshl_b32 s6, s5, 3
	s_lshl_b32 s75, s74, 3
	s_cmpk_gt_i32 s5, 0x1ff
	v_writelane_b32 v250, s6, 27
	s_cselect_b64 s[6:7], -1, 0
	s_add_i32 s76, s2, s81
	v_writelane_b32 v250, s6, 28
	s_cmpk_lt_i32 s5, 0x600
	s_nop 0
	v_writelane_b32 v250, s7, 29
	s_cselect_b64 s[6:7], -1, 0
	s_ashr_i32 s2, s5, 31
	s_lshr_b32 s2, s2, 26
	v_writelane_b32 v250, s6, 30
	s_add_i32 s2, s5, s2
	s_nop 0
	v_writelane_b32 v250, s7, 31
	s_ashr_i32 s6, s2, 6
	s_and_b32 s2, s2, 0xffc0
	v_writelane_b32 v250, s6, 32
	s_sub_i32 s2, s5, s2
	v_writelane_b32 v250, s5, 33
	s_bfe_i32 s5, s2, 0x80000
	s_bfe_u32 s5, s5, 0x4000b
	s_add_i32 s5, s2, s5
	s_bfe_i32 s6, s5, 0x80000
	s_sext_i32_i16 s6, s6
	s_and_b32 s5, s5, 0xf0
	s_lshl_b32 s6, s6, 4
	s_sub_i32 s2, s2, s5
	s_and_b32 s6, s6, 0xffffff00
	s_sext_i32_i8 s2, s2
	v_writelane_b32 v250, s6, 34
	s_lshl_b32 s6, s2, 7
	s_ashr_i32 s7, s6, 31
	v_writelane_b32 v250, s6, 35
	s_lshl_b32 s2, s74, 1
	s_nop 0
	v_writelane_b32 v250, s7, 36
	v_writelane_b32 v250, s2, 37
	s_mul_hi_i32 s2, s80, 0x55555556
	s_lshr_b32 s5, s2, 31
	s_add_i32 s2, s2, s5
	s_mul_i32 s2, s2, 3
	s_sub_i32 s2, s80, s2
	s_sub_i32 s101, s80, s2
	s_mul_hi_u32 s101, s101, 0x55555556
	s_add_i32 s5, s81, 2
	s_mul_hi_u32 s5, s5, 0x55555556
	s_cmp_lg_u32 s2, 0
	s_cselect_b32 s6, s5, 0
	s_add_i32 s101, s101, s6
	s_add_i32 s5, s81, 1
	s_mul_hi_u32 s5, s5, 0x55555556
	s_cmp_eq_u32 s2, 2
	s_cselect_b32 s6, s5, 0
	s_add_i32 s101, s101, s6
	s_cmp_eq_u32 s2, 0
	s_cselect_b64 s[6:7], -1, 0
	v_writelane_b32 v250, s6, 38
	s_nop 1
	v_writelane_b32 v250, s7, 39
	s_add_i32 s6, s101, 0x600
	s_cmpk_lt_i32 s101, 0x600
	s_cselect_b64 s[8:9], -1, 0
	v_writelane_b32 v250, s8, 40
	s_cmpk_lt_i32 s101, 0x200
	s_nop 0
	v_writelane_b32 v250, s9, 41
	s_cselect_b64 s[8:9], -1, 0
	v_writelane_b32 v250, s8, 42
	s_cmpk_gt_i32 s101, 0x1ff
	s_nop 0
	v_writelane_b32 v250, s9, 43
	s_cselect_b64 s[8:9], -1, 0
	v_writelane_b32 v250, s8, 44
	s_add_i32 s5, s101, 0xfffffe00
	s_lshr_b32 s5, s5, 5
	v_writelane_b32 v250, s9, 45
	v_writelane_b32 v250, s5, 46
	s_and_b32 s5, s101, 31
	v_writelane_b32 v250, s5, 47
	s_ashr_i32 s5, s6, 31
	s_lshr_b32 s5, s5, 26
	s_add_i32 s5, s6, s5
	s_ashr_i32 s7, s5, 6
	v_writelane_b32 v250, s7, 48
	s_andn2_b32 s5, s5, 63
	v_writelane_b32 v250, s6, 49
	s_sub_i32 s5, s6, s5
	v_writelane_b32 v250, s5, 50
	s_lshl_b32 s5, s81, 1
	s_cmp_eq_u32 s2, 1
	v_writelane_b32 v250, s5, 51
	s_cselect_b64 s[6:7], -1, 0
	v_writelane_b32 v250, s6, 52
	s_cmp_eq_u32 s2, 2
	s_nop 0
	v_writelane_b32 v250, s7, 53
	s_cselect_b64 s[6:7], -1, 0
	v_writelane_b32 v250, s6, 54
	s_cmpk_lt_i32 s80, 0x100
	s_nop 0
	v_writelane_b32 v250, s7, 55
	s_cselect_b64 s[6:7], -1, 0
	v_writelane_b32 v250, s6, 56
	s_lshr_b32 s2, s13, 31
	s_bfe_i64 s[4:5], s[4:5], 0x100000
	v_writelane_b32 v250, s7, 57
	v_writelane_b32 v250, s13, 58
	v_writelane_b32 v250, s2, 59
	v_writelane_b32 v250, s14, 60
	s_lshl_b32 s2, s14, 19
	v_writelane_b32 v250, s2, 61
	s_lshl_b64 s[4:5], s[4:5], 19
	v_writelane_b32 v250, s4, 62
	s_add_i32 s2, s3, s12
	s_ashr_i32 s3, s2, 31
	v_writelane_b32 v250, s5, 63
	s_load_dwordx2 s[4:5], s[0:1], 0x0
	s_lshr_b32 s3, s3, 27
	s_add_i32 s3, s2, s3
	s_movk_i32 s13, 0x2400
	s_waitcnt lgkmcnt(0)
; __device__ __forceinline__ void conv_tokens(const Frame& F, int l, int wg0) {
;     const int gw = (F.bid - wg0) * NWAVES + F.wave, NGW = (F.G - wg0) * NWAVES, lane = F.lane;
;     const bf16* CV = (const bf16*)(F.ws + WS_CV); bf16* Y = (bf16*)(F.ws + WS_Y);
;     const float* cw = F.in[6] + (size_t)l * 3 * 256 + lane * 4;
;     const f32x4 w0 = *(const f32x4*)cw, w1 = *(const f32x4*)(cw + 256), w2 = *(const f32x4*)(cw + 512);
;     for (int tok0 = gw; tok0 < T; tok0 += 4 * NGW) {
; __device__ __forceinline__ void gates_tiles(const Frame& F, int l, int wg0) {
;     const int NGW = (F.G - wg0) * NWAVES, gw = NGW - 1 - ((F.bid - wg0) * NWAVES + F.wave), fr = F.lane & 15, fq = F.lane >> 4;
;     const bf16* H = (const bf16*)(F.ws + WS_H); const bf16* WG = (const bf16*)(F.ws + WS_WIN) + ((size_t)l * NINP + 3072) * D;
;     for (int rt = gw; rt < T / 16; rt += NGW) {
	v_writelane_b32 v249, s4, 0
	s_nop 1
	v_writelane_b32 v249, s5, 1
	s_load_dwordx4 s[4:7], s[0:1], 0x28
	s_waitcnt lgkmcnt(0)
	v_writelane_b32 v249, s4, 2
	s_nop 1
	v_writelane_b32 v249, s5, 3
	v_writelane_b32 v249, s6, 4
	v_writelane_b32 v249, s7, 5
	s_load_dwordx2 s[4:5], s[0:1], 0x98
	s_waitcnt lgkmcnt(0)
	v_writelane_b32 v249, s4, 6
	s_nop 1
	v_writelane_b32 v249, s5, 7
	v_writelane_b32 v249, s16, 8
	s_ashr_i32 s4, s3, 5
	s_and_b32 s3, s3, 0xffe0
	v_writelane_b32 v249, s17, 9
	s_sub_i32 s3, s2, s3
	v_writelane_b32 v249, s18, 10
	s_bfe_i32 s2, s3, 0x80000
	v_writelane_b32 v249, s19, 11
	s_bfe_u32 s2, s2, 0x3000c
	v_writelane_b32 v249, s20, 12
	s_add_i32 s5, s3, s2
	v_writelane_b32 v249, s21, 13
	s_bfe_i32 s2, s5, 0x80000
	s_and_b32 s5, s5, 0xf8
	v_writelane_b32 v249, s22, 14
	s_sub_i32 s3, s3, s5
	v_writelane_b32 v249, s23, 15
	s_lshl_b32 s4, s4, 3
	s_sext_i32_i16 s6, s2
	s_sext_i32_i8 s3, s3
	v_writelane_b32 v249, s12, 16
	s_add_i32 s3, s4, s3
	s_ashr_i32 s4, s6, 3
	v_writelane_b32 v249, s4, 17
	s_lshr_b32 s2, s6, 3
	v_writelane_b32 v249, s3, 18
	s_lshl_b32 s3, s3, 19
	s_load_dwordx4 s[4:7], s[0:1], 0x60
	v_writelane_b32 v249, s3, 19
	s_bfe_i64 s[2:3], s[2:3], 0x100000
	s_lshl_b64 s[2:3], s[2:3], 19
	v_writelane_b32 v249, s2, 20
	s_lshl_b32 s0, s80, 1
	s_lshl_b32 s1, s10, 5
	v_writelane_b32 v249, s3, 21
	s_waitcnt lgkmcnt(0)
	v_writelane_b32 v249, s4, 22
	s_mul_i32 s2, s10, 24
	s_mov_b64 s[18:19], 0x80
	v_writelane_b32 v249, s5, 23
	v_writelane_b32 v249, s6, 24
	v_writelane_b32 v249, s7, 25
	v_writelane_b32 v249, s0, 26
	s_lshl_b32 s0, s10, 3
	s_sub_i32 s64, 0, s0
	s_lshl_b32 s0, s80, 3
	v_writelane_b32 v249, s0, 27
	s_lshl_b32 s0, s81, 5
	s_sub_i32 s65, s0, s1
	s_lshl_b32 s0, s81, 4
	s_sub_i32 s66, s0, s2
	s_mul_i32 s0, s81, 24
	s_sub_i32 s67, s0, s1
	s_lshl_b32 s0, s81, 3
	s_lshl_b32 s1, s10, 4
	s_sub_i32 s68, s0, s1
	s_lshl_b32 s0, s81, 7
	s_lshl_b32 s1, s80, 7
	s_sub_i32 s1, s0, s1
	s_add_i32 s1, s1, -16
	v_writelane_b32 v249, s1, 28
	s_lshl_b32 s1, s10, 7
	s_sub_i32 s69, s0, s1
	s_lshl_b32 s0, s80, 6
	v_writelane_b32 v249, s0, 29
	s_lshl_b32 s0, s81, 6
	v_writelane_b32 v249, s0, 30
	s_mov_b64 s[0:1], 0
	v_writelane_b32 v249, s0, 31
	s_mov_b32 s17, 0x3fb8aa3b
	s_mov_b32 s21, 0xc2ce8ed0
	v_writelane_b32 v249, s1, 32
	s_add_i32 s0, 0, 0x20020
	v_writelane_b32 v249, s0, 33
	s_add_i32 s0, 0, 0x20024
	v_writelane_b32 v249, s0, 34
	s_add_i32 s0, 0, 0x18800
	v_writelane_b32 v249, s0, 35
	s_add_i32 s0, 0, 0x19000
	v_writelane_b32 v249, s0, 36
	s_add_i32 s0, 0, 0x19800
	v_writelane_b32 v249, s0, 37
	s_add_i32 s0, 0, 0x20140
	v_writelane_b32 v249, s0, 38
	s_mov_b64 s[0:1], 0
	v_writelane_b32 v249, s0, 39
	s_mov_b32 s22, 0x42b17218
	s_mov_b32 s2, 0xf800000
	v_writelane_b32 v249, s1, 40
	s_mov_b32 s0, 0
	v_writelane_b32 v249, s0, 41
	v_writelane_b32 v249, s80, 42
	v_writelane_b32 v249, s81, 43
	v_writelane_b32 v249, s28, 44
	s_mov_b32 s12, 0xf149f2ca
	s_mov_b32 s16, 0x3fd744fd
	v_writelane_b32 v249, s29, 45
	v_writelane_b32 v249, s74, 46
	v_writelane_b32 v249, s75, 47
	v_writelane_b32 v249, s76, 48
	v_writelane_b32 v249, s64, 49
	v_writelane_b32 v249, s65, 50
	v_writelane_b32 v249, s66, 51
	v_writelane_b32 v249, s67, 52
	s_mov_b32 s20, 0x43600000
	s_mov_b32 s23, 0xc0e00000
	v_writelane_b32 v249, s68, 53
	v_writelane_b32 v249, s69, 54
	s_branch .LBB0_537

; #define LAS __attribute__((address_space(3)))
; __device__ __forceinline__ int map_row_rt(int map, int n) { return map == 0 ? n : (map == 1 ? map_row<1>(n) : (map == 3 ? map_row<3>(n) : map_row<2>(n))); }
; __device__ __forceinline__ void witem_store(const Frame& F, const WItem& t, const f32x4 (&v)[16], LAS unsigned char* tile) {
;     const int i = F.lane & 31, hi = F.lane >> 5;
; #pragma unroll
;     for (int j = 0; j < 4; ++j) {
;         u32x4 o;
; #pragma unroll
;         for (int d = 0; d < 4; ++d) { int r = __builtin_amdgcn_cvt_pk_fp8_f32(v[4 * d][j] * t.scale, v[4 * d + 1][j] * t.scale, 0, false);
;             r = __builtin_amdgcn_cvt_pk_fp8_f32(v[4 * d + 2][j] * t.scale, v[4 * d + 3][j] * t.scale, r, true); o[d] = (unsigned)r; }
;         *(LAS u32x4*)(tile + (32 * j + i) * 272 + 32 * F.wave + 16 * hi) = o;
;     }
;     __syncthreads();
;     const int c = F.tid & 15;
; #pragma unroll
;     for (int pass = 0; pass < 4; ++pass) { const int n = (F.tid >> 4) + 32 * pass, rho = (n & 3) * 32 + (n >> 2);
;         const u32x4 o = *(const LAS u32x4*)(tile + rho * 272 + 16 * c);
;         *(u32x4*)(t.WT + (size_t)map_row_rt(t.map, t.n0 + n) * D + t.k0 + 16 * c) = o; }
; __device__ __forceinline__ void fp8_convert_range(const Frame& F, int l, int start, int stride, int limit) {
;     __syncthreads();
;     WItem ta, tb; f32x4 va[16], vb[16];
;     int it = start;
;     bool ha = it < limit && witem_decode(F, l, it, ta);
;     if (ha) witem_load(ta, F.wave, F.lane, va);
.LBB0_1417:
	v_readlane_b32 s4, v248, 1
	v_readlane_b32 s5, v248, 2
	s_movk_i32 s29, 0xc00
	s_and_b64 vcc, exec, s[4:5]
	s_cbranch_vccnz .LBB0_1556
	v_readlane_b32 s3, v248, 0
	v_ashrrev_i32_e32 v137, 4, v0
	s_lshl_b32 s3, s3, 5
	s_waitcnt vmcnt(0)
	v_lshlrev_b32_e32 v8, 5, v137
	v_add_u32_e32 v140, 32, v137
	v_add_u32_e32 v141, 64, v137
	v_add_u32_e32 v142, 0x60, v137
	s_add_i32 s4, s3, 0
	v_and_b32_e32 v8, 0x60, v8
	v_ashrrev_i32_e32 v9, 6, v0
	s_waitcnt vmcnt(8)
	v_lshrrev_b32_e32 v70, 2, v140
	v_lshrrev_b32_e32 v71, 2, v141
	v_lshrrev_b32_e32 v72, 2, v142
	v_and_b32_e32 v6, 31, v0
	v_mov_b32_e32 v7, s4
	s_movk_i32 s4, 0x110
	v_add_u32_e32 v9, v8, v9
	v_add_u32_e32 v70, v8, v70
	v_add_u32_e32 v71, v8, v71
	v_add_u32_e32 v8, v8, v72
	v_mad_u32_u24 v6, v6, s4, v7
	v_mul_lo_u32 v9, v9, s4
	v_mul_lo_u32 v70, v70, s4
	v_mul_lo_u32 v71, v71, s4
	v_mul_lo_u32 v8, v8, s4
	v_readlane_b32 s4, v248, 3
	v_readlane_b32 s5, v248, 4
	s_lshl_b64 s[4:5], s[4:5], 2
	s_add_u32 s4, s78, s4
	s_addc_u32 s5, s79, s5
	s_add_u32 s36, s4, 0x2000
	s_addc_u32 s37, s5, 0
	s_add_u32 s9, s78, 0x58000000
	s_addc_u32 s53, s79, 0
	v_lshlrev_b32_e32 v7, 4, v0
	s_add_u32 s40, s4, 0x2004
	v_and_b32_e32 v134, 0xf0, v7
	v_lshrrev_b32_e32 v72, 1, v0
	s_addc_u32 s41, s5, 0
	v_add_u32_e32 v7, 0, v134
	v_and_b32_e32 v72, 16, v72
	s_add_u32 s54, s78, 0x38000000
	v_lshlrev_b32_e32 v73, 2, v159
	v_mov_b32_e32 v135, v199
	s_addc_u32 s55, s79, 0
	v_or_b32_e32 v143, s3, v72
	v_and_b32_e32 v136, 0x7c, v73
	v_add_u32_e32 v144, v6, v72
	v_add_u32_e32 v145, v7, v9
	v_add_u32_e32 v146, v7, v70
	v_add_u32_e32 v147, v7, v71
	v_add_u32_e32 v148, v7, v8
	v_readlane_b32 s56, v250, 49
	s_mov_b32 s101, 0
	s_branch .LBB0_1421

; #define LAS __attribute__((address_space(3)))
; __device__ __forceinline__ int map_row_rt(int map, int n) { return map == 0 ? n : (map == 1 ? map_row<1>(n) : (map == 3 ? map_row<3>(n) : map_row<2>(n))); }
; __device__ __forceinline__ void witem_store(const Frame& F, const WItem& t, const f32x4 (&v)[16], LAS unsigned char* tile) {
;     ...
;     for (int pass = 0; pass < 4; ++pass) { const int n = (F.tid >> 4) + 32 * pass, rho = (n & 3) * 32 + (n >> 2);
;         const u32x4 o = *(const LAS u32x4*)(tile + rho * 272 + 16 * c);
;         *(u32x4*)(t.WT + (size_t)map_row_rt(t.map, t.n0 + n) * D + t.k0 + 16 * c) = o; }
; __device__ __forceinline__ void fp8_convert_range(const Frame& F, int l, int start, int stride, int limit) {
;     ...
;         witem_store(F, ta, va, F.lds);
;         if (!hb) break;
;         it += 2 * stride;
;         ha = it < limit && witem_decode(F, l, it, ta);
;         if (ha) witem_load(ta, F.wave, F.lane, va);
;         witem_store(F, tb, vb, F.lds + 34816);
.LBB0_1420:
	s_mov_b32 s101, 1
	v_ashrrev_i32_e32 v139, 31, v138
	v_lshlrev_b64 v[138:139], 10, v[138:139]
	v_lshl_add_u64 v[138:139], s[42:43], 0, v[138:139]
	v_lshl_add_u64 v[138:139], v[138:139], 0, s[44:45]
	v_lshl_add_u64 v[138:139], v[138:139], 0, v[134:135]
	s_waitcnt lgkmcnt(0)
	global_store_dwordx4 v[138:139], v[130:133], off
	s_and_b64 vcc, exec, s[48:49]
	s_cbranch_vccnz .LBB0_1556

; __device__ __forceinline__ float w_qscale(float wmax) { return exp2f(floorf(log2f(128.f / fmaxf(wmax, 1e-30f)))); }
; __device__ __forceinline__ bool witem_decode(const Frame& F, int l, int it, WItem& t) {
;     constexpr int I_GU = 4 * 16, I_DN = 4 * 8, N_GU = NE * I_GU, N_DN = NE * I_DN;
;     const float* wmax = (const float*)((const unsigned*)(F.ws + WS_CTL) + CW_WMAX);
;     int r = it, nblk, item;
;     if (r < N_GU) { const int le = l * NE + r / I_GU; t.W = F.in[16] + (size_t)le * D * 2048; t.WT = (unsigned char*)(F.ws + WS_WGU) + (size_t)le * 2048 * D; t.N = 2048; t.map = 1; nblk = 16; item = r % I_GU; t.scale = w_qscale(wmax[l * 2 + 0]); }
;     else if ((r -= N_GU) < N_DN) { const int le = l * NE + r / I_DN; t.W = F.in[18] + (size_t)le * FF * D; t.WT = (unsigned char*)(F.ws + WS_WDN) + (size_t)le * D * FF; t.N = D; t.map = 3; nblk = 8; item = r % I_DN; t.scale = w_qscale(wmax[l * 2 + 1]); }
;     else return false;
;     t.k0 = 256 * (item / nblk); t.n0 = 128 * (item % nblk); return true;
; }
; __device__ __forceinline__ void witem_load(const WItem& t, int wave, int lane, f32x4 (&v)[16]) {
;     const float* wp = t.W + (size_t)(t.k0 + 32 * wave + 16 * (lane >> 5)) * t.N + t.n0 + 4 * (lane & 31);
; #pragma unroll
;     for (int q = 0; q < 16; ++q) v[q] = __builtin_nontemporal_load((const f32x4*)(wp + (size_t)q * t.N));
; }
; __device__ __forceinline__ void fp8_convert_range(const Frame& F, int l, int start, int stride, int limit) {
;     ...
;     while (ha) {
;         const bool hb = it + stride < limit && witem_decode(F, l, it + stride, tb);
;         if (hb) witem_load(tb, F.wave, F.lane, vb);
;         witem_store(F, ta, va, F.lds);
;         if (!hb) break;
;         it += 2 * stride;
;         ha = it < limit && witem_decode(F, l, it, ta);
;         if (ha) witem_load(ta, F.wave, F.lane, va);
;         witem_store(F, tb, vb, F.lds + 34816);
.LBB0_1427:
	s_load_dword s100, s[4:5], 0x0
	s_mov_b32 s7, 0x43000000
	v_lshlrev_b32_e32 v198, 2, v136
	s_waitcnt lgkmcnt(0)
	v_mov_b32_e32 v6, s100
	v_max_f32_e32 v6, v6, v6
	v_max_f32_e32 v6, 0xda24260, v6
	v_div_scale_f32 v7, s[4:5], v6, v6, s7
	v_rcp_f32_e32 v8, v7
	s_mov_b32 s4, 0x800000
	v_fma_f32 v9, -v7, v8, 1.0
	v_fmac_f32_e32 v8, v9, v8
	v_div_scale_f32 v9, vcc, s7, v6, s7
	v_mul_f32_e32 v70, v9, v8
	v_fma_f32 v71, -v7, v70, v9
	v_fmac_f32_e32 v70, v71, v8
	v_fma_f32 v7, -v7, v70, v9
	v_div_fmas_f32 v7, v7, v8, v70
	v_div_fixup_f32 v6, v7, v6, s7
	v_cmp_gt_f32_e32 vcc, s4, v6
	s_and_b64 s[4:5], vcc, exec
	s_cselect_b32 s4, 32, 0
	v_ldexp_f32 v6, v6, s4
	v_log_f32_e32 v6, v6
	v_cndmask_b32_e32 v7, 0, v232, vcc
	s_mov_b32 s4, 0xc2fc0000
	v_sub_f32_e32 v6, v6, v7
	v_floor_f32_e32 v6, v6
	v_cmp_gt_f32_e32 vcc, s4, v6
	s_and_b64 s[4:5], vcc, exec
	s_cselect_b32 s4, 0xffffffc0, 0
	v_cndmask_b32_e32 v7, 0, v233, vcc
	v_add_f32_e32 v6, v6, v7
	v_exp_f32_e32 v6, v6
	v_cvt_f32_ubyte0_e32 v7, s6
	v_rcp_iflag_f32_e32 v8, v7
	v_ldexp_f32 v149, v6, s4
	s_sext_i32_i8 s4, s3
	v_cvt_f32_i32_e32 v6, s4
	s_ashr_i32 s5, s4, 30
	s_or_b32 s7, s5, 1
	v_mul_f32_e32 v8, v6, v8
	v_trunc_f32_e32 v8, v8
	v_fma_f32 v6, -v8, v7, v6
	v_cvt_i32_f32_e32 v8, v8
	v_cmp_ge_f32_e64 s[4:5], |v6|, v7
	s_and_b64 s[4:5], s[4:5], exec
	s_cselect_b32 s4, s7, 0
	v_readfirstlane_b32 s5, v8
	s_add_i32 s4, s5, s4
	s_sext_i32_i8 s5, s4
	s_mul_i32 s4, s4, s6
	s_lshl_b32 s44, s5, 8
	s_sub_i32 s3, s3, s4
	s_sext_i32_i8 s3, s3
	v_add_u32_e32 v6, s44, v143
	s_lshl_b32 s46, s3, 7
	v_mad_i64_i32 v[6:7], s[4:5], s26, v6, 0
	v_lshl_add_u64 v[6:7], v[6:7], 2, s[50:51]
	s_ashr_i32 s47, s46, 31
	v_lshl_add_u64 v[6:7], s[46:47], 2, v[6:7]
	v_lshl_add_u64 v[70:71], v[6:7], 0, v[198:199]
	s_lshl_b32 s34, s26, 2
	v_lshl_add_u64 v[74:75], v[70:71], 0, s[34:35]
	v_lshl_add_u64 v[78:79], v[74:75], 0, s[34:35]
	v_lshl_add_u64 v[82:83], v[78:79], 0, s[34:35]
	v_lshl_add_u64 v[86:87], v[82:83], 0, s[34:35]
	v_lshl_add_u64 v[90:91], v[86:87], 0, s[34:35]
	v_lshl_add_u64 v[94:95], v[90:91], 0, s[34:35]
	v_lshl_add_u64 v[98:99], v[94:95], 0, s[34:35]
	v_lshl_add_u64 v[102:103], v[98:99], 0, s[34:35]
	v_lshl_add_u64 v[106:107], v[102:103], 0, s[34:35]
	v_lshl_add_u64 v[110:111], v[106:107], 0, s[34:35]
	v_lshl_add_u64 v[114:115], v[110:111], 0, s[34:35]
	v_lshl_add_u64 v[118:119], v[114:115], 0, s[34:35]
	v_lshl_add_u64 v[122:123], v[118:119], 0, s[34:35]
	v_lshl_add_u64 v[126:127], v[122:123], 0, s[34:35]
	global_load_dwordx4 v[6:9], v[70:71], off nt
	s_nop 0
	global_load_dwordx4 v[70:73], v[74:75], off nt
	s_nop 0
	global_load_dwordx4 v[74:77], v[78:79], off nt
	s_nop 0
	global_load_dwordx4 v[78:81], v[82:83], off nt
	s_nop 0
	global_load_dwordx4 v[82:85], v[86:87], off nt
	s_nop 0
	global_load_dwordx4 v[86:89], v[90:91], off nt
	s_nop 0
	global_load_dwordx4 v[90:93], v[94:95], off nt
	s_nop 0
	global_load_dwordx4 v[94:97], v[98:99], off nt
	s_nop 0
	global_load_dwordx4 v[98:101], v[102:103], off nt
	s_nop 0
	global_load_dwordx4 v[102:105], v[106:107], off nt
	s_nop 0
	global_load_dwordx4 v[106:109], v[110:111], off nt
	s_nop 0
	global_load_dwordx4 v[110:113], v[114:115], off nt
	s_nop 0
	global_load_dwordx4 v[114:117], v[118:119], off nt
	s_nop 0
	global_load_dwordx4 v[118:121], v[122:123], off nt
	s_nop 0
	global_load_dwordx4 v[122:125], v[126:127], off nt
	v_lshl_add_u64 v[126:127], v[126:127], 0, s[34:35]
	global_load_dwordx4 v[126:129], v[126:127], off nt
	s_cmp_lg_u32 s101, 0
	s_cbranch_scc1 .Lcvx_0
	s_waitcnt vmcnt(16)
	v_mul_f32_e32 v131, v2, v1
	s_branch .Lcvw_0
.Lcvx_0:
	s_waitcnt vmcnt(20)
	v_mul_f32_e32 v131, v2, v1
	s_branch .Lcvw_0

; __device__ __forceinline__ float w_qscale(float wmax) { return exp2f(floorf(log2f(128.f / fmaxf(wmax, 1e-30f)))); }
; __device__ __forceinline__ bool witem_decode(const Frame& F, int l, int it, WItem& t) {
;     constexpr int I_GU = 4 * 16, I_DN = 4 * 8, N_GU = NE * I_GU, N_DN = NE * I_DN;
;     const float* wmax = (const float*)((const unsigned*)(F.ws + WS_CTL) + CW_WMAX);
;     int r = it, nblk, item;
;     if (r < N_GU) { const int le = l * NE + r / I_GU; t.W = F.in[16] + (size_t)le * D * 2048; t.WT = (unsigned char*)(F.ws + WS_WGU) + (size_t)le * 2048 * D; t.N = 2048; t.map = 1; nblk = 16; item = r % I_GU; t.scale = w_qscale(wmax[l * 2 + 0]); }
;     else if ((r -= N_GU) < N_DN) { const int le = l * NE + r / I_DN; t.W = F.in[18] + (size_t)le * FF * D; t.WT = (unsigned char*)(F.ws + WS_WDN) + (size_t)le * D * FF; t.N = D; t.map = 3; nblk = 8; item = r % I_DN; t.scale = w_qscale(wmax[l * 2 + 1]); }
;     else return false;
;     t.k0 = 256 * (item / nblk); t.n0 = 128 * (item % nblk); return true;
; }
; __device__ __forceinline__ void witem_load(const WItem& t, int wave, int lane, f32x4 (&v)[16]) {
;     const float* wp = t.W + (size_t)(t.k0 + 32 * wave + 16 * (lane >> 5)) * t.N + t.n0 + 4 * (lane & 31);
; #pragma unroll
;     for (int q = 0; q < 16; ++q) v[q] = __builtin_nontemporal_load((const f32x4*)(wp + (size_t)q * t.N));
; }
; __device__ __forceinline__ void fp8_convert_range(const Frame& F, int l, int start, int stride, int limit) {
;     ...
;     while (ha) {
;         const bool hb = it + stride < limit && witem_decode(F, l, it + stride, tb);
;         if (hb) witem_load(tb, F.wave, F.lane, vb);
;         witem_store(F, ta, va, F.lds);
;         if (!hb) break;
;         it += 2 * stride;
;         ha = it < limit && witem_decode(F, l, it, ta);
;         if (ha) witem_load(ta, F.wave, F.lane, va);
;         witem_store(F, tb, vb, F.lds + 34816);
.LBB0_1496:
	s_load_dword s100, s[4:5], 0x0
	s_mov_b32 s7, 0x43000000
	v_lshlrev_b32_e32 v198, 2, v136
	s_waitcnt lgkmcnt(0)
	v_mov_b32_e32 v1, s100
	v_max_f32_e32 v1, v1, v1
	v_max_f32_e32 v1, 0xda24260, v1
	v_div_scale_f32 v2, s[4:5], v1, v1, s7
	v_rcp_f32_e32 v3, v2
	s_mov_b32 s4, 0x800000
	v_fma_f32 v4, -v2, v3, 1.0
	v_fmac_f32_e32 v3, v4, v3
	v_div_scale_f32 v4, vcc, s7, v1, s7
	v_mul_f32_e32 v5, v4, v3
	v_fma_f32 v10, -v2, v5, v4
	v_fmac_f32_e32 v5, v10, v3
	v_fma_f32 v2, -v2, v5, v4
	v_div_fmas_f32 v2, v2, v3, v5
	v_div_fixup_f32 v1, v2, v1, s7
	v_cmp_gt_f32_e32 vcc, s4, v1
	s_and_b64 s[4:5], vcc, exec
	s_cselect_b32 s4, 32, 0
	v_ldexp_f32 v1, v1, s4
	v_log_f32_e32 v1, v1
	v_cndmask_b32_e32 v2, 0, v232, vcc
	s_mov_b32 s4, 0xc2fc0000
	v_cvt_f32_ubyte0_e32 v3, s6
	v_sub_f32_e32 v1, v1, v2
	v_floor_f32_e32 v1, v1
	v_cmp_gt_f32_e32 vcc, s4, v1
	s_and_b64 s[4:5], vcc, exec
	s_cselect_b32 s4, 0xffffffc0, 0
	v_cndmask_b32_e32 v2, 0, v233, vcc
	v_add_f32_e32 v1, v1, v2
	v_exp_f32_e32 v1, v1
	v_rcp_iflag_f32_e32 v4, v3
	v_ldexp_f32 v1, v1, s4
	s_sext_i32_i8 s4, s3
	v_cvt_f32_i32_e32 v2, s4
	s_ashr_i32 s5, s4, 30
	s_or_b32 s7, s5, 1
	v_mul_f32_e32 v4, v2, v4
	v_trunc_f32_e32 v4, v4
	v_fma_f32 v2, -v4, v3, v2
	v_cvt_i32_f32_e32 v4, v4
	v_cmp_ge_f32_e64 s[4:5], |v2|, v3
	s_and_b64 s[4:5], s[4:5], exec
	s_cselect_b32 s4, s7, 0
	v_readfirstlane_b32 s5, v4
	s_add_i32 s4, s5, s4
	s_sext_i32_i8 s5, s4
	s_mul_i32 s4, s4, s6
	s_lshl_b32 s14, s5, 8
	s_sub_i32 s3, s3, s4
	s_sext_i32_i8 s3, s3
	v_add_u32_e32 v2, s14, v143
	s_lshl_b32 s28, s3, 7
	v_mad_i64_i32 v[2:3], s[4:5], s26, v2, 0
	v_lshl_add_u64 v[2:3], v[2:3], 2, s[50:51]
	s_ashr_i32 s29, s28, 31
	v_lshl_add_u64 v[2:3], s[28:29], 2, v[2:3]
	v_lshl_add_u64 v[10:11], v[2:3], 0, v[198:199]
	s_lshl_b32 s34, s26, 2
	v_lshl_add_u64 v[14:15], v[10:11], 0, s[34:35]
	v_lshl_add_u64 v[18:19], v[14:15], 0, s[34:35]
	v_lshl_add_u64 v[22:23], v[18:19], 0, s[34:35]
	v_lshl_add_u64 v[26:27], v[22:23], 0, s[34:35]
	v_lshl_add_u64 v[30:31], v[26:27], 0, s[34:35]
	v_lshl_add_u64 v[34:35], v[30:31], 0, s[34:35]
	v_lshl_add_u64 v[38:39], v[34:35], 0, s[34:35]
	v_lshl_add_u64 v[42:43], v[38:39], 0, s[34:35]
	v_lshl_add_u64 v[46:47], v[42:43], 0, s[34:35]
	v_lshl_add_u64 v[50:51], v[46:47], 0, s[34:35]
	v_lshl_add_u64 v[54:55], v[50:51], 0, s[34:35]
	v_lshl_add_u64 v[58:59], v[54:55], 0, s[34:35]
	v_lshl_add_u64 v[62:63], v[58:59], 0, s[34:35]
	v_lshl_add_u64 v[66:67], v[62:63], 0, s[34:35]
	global_load_dwordx4 v[2:5], v[10:11], off nt
	s_movk_i32 s29, 0xc00
	global_load_dwordx4 v[10:13], v[14:15], off nt
	s_nop 0
	global_load_dwordx4 v[14:17], v[18:19], off nt
	s_nop 0
	global_load_dwordx4 v[18:21], v[22:23], off nt
	s_nop 0
	global_load_dwordx4 v[22:25], v[26:27], off nt
	s_nop 0
	global_load_dwordx4 v[26:29], v[30:31], off nt
	s_nop 0
	global_load_dwordx4 v[30:33], v[34:35], off nt
	s_nop 0
	global_load_dwordx4 v[34:37], v[38:39], off nt
	s_nop 0
	global_load_dwordx4 v[38:41], v[42:43], off nt
	s_nop 0
	global_load_dwordx4 v[42:45], v[46:47], off nt
	s_nop 0
	global_load_dwordx4 v[46:49], v[50:51], off nt
	s_nop 0
	global_load_dwordx4 v[50:53], v[54:55], off nt
	s_nop 0
	global_load_dwordx4 v[54:57], v[58:59], off nt
	s_nop 0
	global_load_dwordx4 v[58:61], v[62:63], off nt
	s_nop 0
	global_load_dwordx4 v[62:65], v[66:67], off nt
	v_lshl_add_u64 v[66:67], v[66:67], 0, s[34:35]
	global_load_dwordx4 v[66:69], v[66:67], off nt
	s_waitcnt vmcnt(20)
	s_branch .Lcvw_1

; #define LAS __attribute__((address_space(3)))
; __device__ __forceinline__ int map_row_rt(int map, int n) { return map == 0 ? n : (map == 1 ? map_row<1>(n) : (map == 3 ? map_row<3>(n) : map_row<2>(n))); }
; __device__ __forceinline__ void witem_store(const Frame& F, const WItem& t, const f32x4 (&v)[16], LAS unsigned char* tile) {
;     const int i = F.lane & 31, hi = F.lane >> 5;
; #pragma unroll
;     for (int j = 0; j < 4; ++j) {
;         u32x4 o;
; #pragma unroll
;         for (int d = 0; d < 4; ++d) { int r = __builtin_amdgcn_cvt_pk_fp8_f32(v[4 * d][j] * t.scale, v[4 * d + 1][j] * t.scale, 0, false);
;             r = __builtin_amdgcn_cvt_pk_fp8_f32(v[4 * d + 2][j] * t.scale, v[4 * d + 3][j] * t.scale, r, true); o[d] = (unsigned)r; }
;         *(LAS u32x4*)(tile + (32 * j + i) * 272 + 32 * F.wave + 16 * hi) = o;
;     }
;     __syncthreads();
;     const int c = F.tid & 15;
; #pragma unroll
;     for (int pass = 0; pass < 4; ++pass) { const int n = (F.tid >> 4) + 32 * pass, rho = (n & 3) * 32 + (n >> 2);
;         const u32x4 o = *(const LAS u32x4*)(tile + rho * 272 + 16 * c);
;         *(u32x4*)(t.WT + (size_t)map_row_rt(t.map, t.n0 + n) * D + t.k0 + 16 * c) = o; }
; __device__ __forceinline__ void fp8_convert_range(const Frame& F, int l, int start, int stride, int limit) {
;     __syncthreads();
;     WItem ta, tb; f32x4 va[16], vb[16];
;     int it = start;
;     bool ha = it < limit && witem_decode(F, l, it, ta);
;     if (ha) witem_load(ta, F.wave, F.lane, va);
.LBB0_1603:
	v_readlane_b32 s4, v248, 1
	v_readlane_b32 s5, v248, 2
	s_and_b64 vcc, exec, s[4:5]
	s_cbranch_vccnz .LBB0_1742
	v_readlane_b32 s3, v248, 0
	v_ashrrev_i32_e32 v137, 4, v0
	s_lshl_b32 s3, s3, 5
	s_waitcnt vmcnt(0)
	v_lshlrev_b32_e32 v8, 5, v137
	v_add_u32_e32 v140, 32, v137
	v_add_u32_e32 v141, 64, v137
	v_add_u32_e32 v142, 0x60, v137
	s_add_i32 s4, s3, 0
	v_and_b32_e32 v8, 0x60, v8
	v_ashrrev_i32_e32 v9, 6, v0
	s_waitcnt vmcnt(8)
	v_lshrrev_b32_e32 v70, 2, v140
	v_lshrrev_b32_e32 v71, 2, v141
	v_lshrrev_b32_e32 v72, 2, v142
	v_and_b32_e32 v6, 31, v0
	v_mov_b32_e32 v7, s4
	s_movk_i32 s4, 0x110
	v_add_u32_e32 v9, v8, v9
	v_add_u32_e32 v70, v8, v70
	v_add_u32_e32 v71, v8, v71
	v_add_u32_e32 v8, v8, v72
	v_mad_u32_u24 v6, v6, s4, v7
	v_mul_lo_u32 v9, v9, s4
	v_mul_lo_u32 v70, v70, s4
	v_mul_lo_u32 v71, v71, s4
	v_mul_lo_u32 v8, v8, s4
	v_readlane_b32 s4, v248, 3
	v_readlane_b32 s5, v248, 4
	s_lshl_b64 s[4:5], s[4:5], 2
	s_add_u32 s4, s78, s4
	s_addc_u32 s5, s79, s5
	s_add_u32 s40, s4, 0x2000
	s_addc_u32 s41, s5, 0
	s_add_u32 s9, s78, 0x58000000
	s_addc_u32 s54, s79, 0
	v_lshlrev_b32_e32 v7, 4, v0
	s_add_u32 s42, s4, 0x2004
	v_and_b32_e32 v134, 0xf0, v7
	v_lshrrev_b32_e32 v72, 1, v0
	s_addc_u32 s43, s5, 0
	v_add_u32_e32 v7, 0, v134
	v_and_b32_e32 v72, 16, v72
	s_add_u32 s55, s78, 0x38000000
	v_lshlrev_b32_e32 v73, 2, v159
	v_mov_b32_e32 v135, v199
	s_addc_u32 s56, s79, 0
	v_or_b32_e32 v143, s3, v72
	v_and_b32_e32 v136, 0x7c, v73
	v_add_u32_e32 v144, v6, v72
	v_add_u32_e32 v145, v7, v9
	v_add_u32_e32 v146, v7, v70
	v_add_u32_e32 v147, v7, v71
	v_add_u32_e32 v148, v7, v8
	v_readlane_b32 s57, v250, 49
	v_readlane_b32 s30, v248, 5
	s_mov_b32 s101, 0
	s_branch .LBB0_1607

; #define LAS __attribute__((address_space(3)))
; __device__ __forceinline__ int map_row_rt(int map, int n) { return map == 0 ? n : (map == 1 ? map_row<1>(n) : (map == 3 ? map_row<3>(n) : map_row<2>(n))); }
; __device__ __forceinline__ void witem_store(const Frame& F, const WItem& t, const f32x4 (&v)[16], LAS unsigned char* tile) {
;     ...
;     for (int pass = 0; pass < 4; ++pass) { const int n = (F.tid >> 4) + 32 * pass, rho = (n & 3) * 32 + (n >> 2);
;         const u32x4 o = *(const LAS u32x4*)(tile + rho * 272 + 16 * c);
;         *(u32x4*)(t.WT + (size_t)map_row_rt(t.map, t.n0 + n) * D + t.k0 + 16 * c) = o; }
; __device__ __forceinline__ void fp8_convert_range(const Frame& F, int l, int start, int stride, int limit) {
;     ...
;         witem_store(F, ta, va, F.lds);
;         if (!hb) break;
;         it += 2 * stride;
;         ha = it < limit && witem_decode(F, l, it, ta);
;         if (ha) witem_load(ta, F.wave, F.lane, va);
;         witem_store(F, tb, vb, F.lds + 34816);
.LBB0_1606:
	s_mov_b32 s101, 1
	v_ashrrev_i32_e32 v139, 31, v138
	v_lshlrev_b64 v[138:139], 10, v[138:139]
	v_lshl_add_u64 v[138:139], s[44:45], 0, v[138:139]
	v_lshl_add_u64 v[138:139], v[138:139], 0, s[46:47]
	v_lshl_add_u64 v[138:139], v[138:139], 0, v[134:135]
	s_waitcnt lgkmcnt(0)
	global_store_dwordx4 v[138:139], v[130:133], off
	s_and_b64 vcc, exec, s[50:51]
	s_cbranch_vccnz .LBB0_1742

; __device__ __forceinline__ float w_qscale(float wmax) { return exp2f(floorf(log2f(128.f / fmaxf(wmax, 1e-30f)))); }
; __device__ __forceinline__ bool witem_decode(const Frame& F, int l, int it, WItem& t) {
;     constexpr int I_GU = 4 * 16, I_DN = 4 * 8, N_GU = NE * I_GU, N_DN = NE * I_DN;
;     const float* wmax = (const float*)((const unsigned*)(F.ws + WS_CTL) + CW_WMAX);
;     int r = it, nblk, item;
;     if (r < N_GU) { const int le = l * NE + r / I_GU; t.W = F.in[16] + (size_t)le * D * 2048; t.WT = (unsigned char*)(F.ws + WS_WGU) + (size_t)le * 2048 * D; t.N = 2048; t.map = 1; nblk = 16; item = r % I_GU; t.scale = w_qscale(wmax[l * 2 + 0]); }
;     else if ((r -= N_GU) < N_DN) { const int le = l * NE + r / I_DN; t.W = F.in[18] + (size_t)le * FF * D; t.WT = (unsigned char*)(F.ws + WS_WDN) + (size_t)le * D * FF; t.N = D; t.map = 3; nblk = 8; item = r % I_DN; t.scale = w_qscale(wmax[l * 2 + 1]); }
;     else return false;
;     t.k0 = 256 * (item / nblk); t.n0 = 128 * (item % nblk); return true;
; }
; __device__ __forceinline__ void witem_load(const WItem& t, int wave, int lane, f32x4 (&v)[16]) {
;     const float* wp = t.W + (size_t)(t.k0 + 32 * wave + 16 * (lane >> 5)) * t.N + t.n0 + 4 * (lane & 31);
; #pragma unroll
;     for (int q = 0; q < 16; ++q) v[q] = __builtin_nontemporal_load((const f32x4*)(wp + (size_t)q * t.N));
; }
; __device__ __forceinline__ void fp8_convert_range(const Frame& F, int l, int start, int stride, int limit) {
;     ...
;     while (ha) {
;         const bool hb = it + stride < limit && witem_decode(F, l, it + stride, tb);
;         if (hb) witem_load(tb, F.wave, F.lane, vb);
;         witem_store(F, ta, va, F.lds);
;         if (!hb) break;
;         it += 2 * stride;
;         ha = it < limit && witem_decode(F, l, it, ta);
;         if (ha) witem_load(ta, F.wave, F.lane, va);
;         witem_store(F, tb, vb, F.lds + 34816);
.LBB0_1613:
	s_load_dword s100, s[4:5], 0x0
	s_mov_b32 s7, 0x43000000
	v_lshlrev_b32_e32 v198, 2, v136
	s_waitcnt lgkmcnt(0)
	v_mov_b32_e32 v6, s100
	v_max_f32_e32 v6, v6, v6
	v_max_f32_e32 v6, 0xda24260, v6
	v_div_scale_f32 v7, s[4:5], v6, v6, s7
	v_rcp_f32_e32 v8, v7
	s_mov_b32 s4, 0x800000
	v_fma_f32 v9, -v7, v8, 1.0
	v_fmac_f32_e32 v8, v9, v8
	v_div_scale_f32 v9, vcc, s7, v6, s7
	v_mul_f32_e32 v70, v9, v8
	v_fma_f32 v71, -v7, v70, v9
	v_fmac_f32_e32 v70, v71, v8
	v_fma_f32 v7, -v7, v70, v9
	v_div_fmas_f32 v7, v7, v8, v70
	v_div_fixup_f32 v6, v7, v6, s7
	v_cmp_gt_f32_e32 vcc, s4, v6
	s_and_b64 s[4:5], vcc, exec
	s_cselect_b32 s4, 32, 0
	v_ldexp_f32 v6, v6, s4
	v_log_f32_e32 v6, v6
	v_cndmask_b32_e32 v7, 0, v232, vcc
	s_mov_b32 s4, 0xc2fc0000
	v_sub_f32_e32 v6, v6, v7
	v_floor_f32_e32 v6, v6
	v_cmp_gt_f32_e32 vcc, s4, v6
	s_and_b64 s[4:5], vcc, exec
	s_cselect_b32 s4, 0xffffffc0, 0
	v_cndmask_b32_e32 v7, 0, v233, vcc
	v_add_f32_e32 v6, v6, v7
	v_exp_f32_e32 v6, v6
	v_cvt_f32_ubyte0_e32 v7, s6
	v_rcp_iflag_f32_e32 v8, v7
	v_ldexp_f32 v149, v6, s4
	s_sext_i32_i8 s4, s3
	v_cvt_f32_i32_e32 v6, s4
	s_ashr_i32 s5, s4, 30
	s_or_b32 s7, s5, 1
	v_mul_f32_e32 v8, v6, v8
	v_trunc_f32_e32 v8, v8
	v_fma_f32 v6, -v8, v7, v6
	v_cvt_i32_f32_e32 v8, v8
	v_cmp_ge_f32_e64 s[4:5], |v6|, v7
	s_and_b64 s[4:5], s[4:5], exec
	s_cselect_b32 s4, s7, 0
	v_readfirstlane_b32 s5, v8
	s_add_i32 s4, s5, s4
	s_sext_i32_i8 s5, s4
	s_mul_i32 s4, s4, s6
	s_lshl_b32 s46, s5, 8
	s_sub_i32 s3, s3, s4
	s_sext_i32_i8 s3, s3
	v_add_u32_e32 v6, s46, v143
	s_lshl_b32 s48, s3, 7
	v_mad_i64_i32 v[6:7], s[4:5], s26, v6, 0
	v_lshl_add_u64 v[6:7], v[6:7], 2, s[52:53]
	s_ashr_i32 s49, s48, 31
	v_lshl_add_u64 v[6:7], s[48:49], 2, v[6:7]
	v_lshl_add_u64 v[70:71], v[6:7], 0, v[198:199]
	s_lshl_b32 s34, s26, 2
	v_lshl_add_u64 v[74:75], v[70:71], 0, s[34:35]
	v_lshl_add_u64 v[78:79], v[74:75], 0, s[34:35]
	v_lshl_add_u64 v[82:83], v[78:79], 0, s[34:35]
	v_lshl_add_u64 v[86:87], v[82:83], 0, s[34:35]
	v_lshl_add_u64 v[90:91], v[86:87], 0, s[34:35]
	v_lshl_add_u64 v[94:95], v[90:91], 0, s[34:35]
	v_lshl_add_u64 v[98:99], v[94:95], 0, s[34:35]
	v_lshl_add_u64 v[102:103], v[98:99], 0, s[34:35]
	v_lshl_add_u64 v[106:107], v[102:103], 0, s[34:35]
	v_lshl_add_u64 v[110:111], v[106:107], 0, s[34:35]
	v_lshl_add_u64 v[114:115], v[110:111], 0, s[34:35]
	v_lshl_add_u64 v[118:119], v[114:115], 0, s[34:35]
	v_lshl_add_u64 v[122:123], v[118:119], 0, s[34:35]
	v_lshl_add_u64 v[126:127], v[122:123], 0, s[34:35]
	global_load_dwordx4 v[6:9], v[70:71], off nt
	s_nop 0
	global_load_dwordx4 v[70:73], v[74:75], off nt
	s_nop 0
	global_load_dwordx4 v[74:77], v[78:79], off nt
	s_nop 0
	global_load_dwordx4 v[78:81], v[82:83], off nt
	s_nop 0
	global_load_dwordx4 v[82:85], v[86:87], off nt
	s_nop 0
	global_load_dwordx4 v[86:89], v[90:91], off nt
	s_nop 0
	global_load_dwordx4 v[90:93], v[94:95], off nt
	s_nop 0
	global_load_dwordx4 v[94:97], v[98:99], off nt
	s_nop 0
	global_load_dwordx4 v[98:101], v[102:103], off nt
	s_nop 0
	global_load_dwordx4 v[102:105], v[106:107], off nt
	s_nop 0
	global_load_dwordx4 v[106:109], v[110:111], off nt
	s_nop 0
	global_load_dwordx4 v[110:113], v[114:115], off nt
	s_nop 0
	global_load_dwordx4 v[114:117], v[118:119], off nt
	s_nop 0
	global_load_dwordx4 v[118:121], v[122:123], off nt
	s_nop 0
	global_load_dwordx4 v[122:125], v[126:127], off nt
	v_lshl_add_u64 v[126:127], v[126:127], 0, s[34:35]
	global_load_dwordx4 v[126:129], v[126:127], off nt
	s_cmp_lg_u32 s101, 0
	s_cbranch_scc1 .Lcvx_2
	s_waitcnt vmcnt(16)
	v_mul_f32_e32 v131, v2, v1
	s_branch .Lcvw_2

; __device__ __forceinline__ float w_qscale(float wmax) { return exp2f(floorf(log2f(128.f / fmaxf(wmax, 1e-30f)))); }
; __device__ __forceinline__ bool witem_decode(const Frame& F, int l, int it, WItem& t) {
;     constexpr int I_GU = 4 * 16, I_DN = 4 * 8, N_GU = NE * I_GU, N_DN = NE * I_DN;
;     const float* wmax = (const float*)((const unsigned*)(F.ws + WS_CTL) + CW_WMAX);
;     int r = it, nblk, item;
;     if (r < N_GU) { const int le = l * NE + r / I_GU; t.W = F.in[16] + (size_t)le * D * 2048; t.WT = (unsigned char*)(F.ws + WS_WGU) + (size_t)le * 2048 * D; t.N = 2048; t.map = 1; nblk = 16; item = r % I_GU; t.scale = w_qscale(wmax[l * 2 + 0]); }
;     else if ((r -= N_GU) < N_DN) { const int le = l * NE + r / I_DN; t.W = F.in[18] + (size_t)le * FF * D; t.WT = (unsigned char*)(F.ws + WS_WDN) + (size_t)le * D * FF; t.N = D; t.map = 3; nblk = 8; item = r % I_DN; t.scale = w_qscale(wmax[l * 2 + 1]); }
;     else return false;
;     t.k0 = 256 * (item / nblk); t.n0 = 128 * (item % nblk); return true;
; }
; __device__ __forceinline__ void witem_load(const WItem& t, int wave, int lane, f32x4 (&v)[16]) {
;     const float* wp = t.W + (size_t)(t.k0 + 32 * wave + 16 * (lane >> 5)) * t.N + t.n0 + 4 * (lane & 31);
; #pragma unroll
;     for (int q = 0; q < 16; ++q) v[q] = __builtin_nontemporal_load((const f32x4*)(wp + (size_t)q * t.N));
; }
; __device__ __forceinline__ void fp8_convert_range(const Frame& F, int l, int start, int stride, int limit) {
;     ...
;     while (ha) {
;         const bool hb = it + stride < limit && witem_decode(F, l, it + stride, tb);
;         if (hb) witem_load(tb, F.wave, F.lane, vb);
;         witem_store(F, ta, va, F.lds);
;         if (!hb) break;
;         it += 2 * stride;
;         ha = it < limit && witem_decode(F, l, it, ta);
;         if (ha) witem_load(ta, F.wave, F.lane, va);
;         witem_store(F, tb, vb, F.lds + 34816);
.LBB0_1682:
	s_load_dword s100, s[4:5], 0x0
	s_mov_b32 s7, 0x43000000
	v_lshlrev_b32_e32 v198, 2, v136
	s_waitcnt lgkmcnt(0)
	v_mov_b32_e32 v1, s100
	v_max_f32_e32 v1, v1, v1
	v_max_f32_e32 v1, 0xda24260, v1
	v_div_scale_f32 v2, s[4:5], v1, v1, s7
	v_rcp_f32_e32 v3, v2
	s_mov_b32 s4, 0x800000
	v_fma_f32 v4, -v2, v3, 1.0
	v_fmac_f32_e32 v3, v4, v3
	v_div_scale_f32 v4, vcc, s7, v1, s7
	v_mul_f32_e32 v5, v4, v3
	v_fma_f32 v10, -v2, v5, v4
	v_fmac_f32_e32 v5, v10, v3
	v_fma_f32 v2, -v2, v5, v4
	v_div_fmas_f32 v2, v2, v3, v5
	v_div_fixup_f32 v1, v2, v1, s7
	v_cmp_gt_f32_e32 vcc, s4, v1
	s_and_b64 s[4:5], vcc, exec
	s_cselect_b32 s4, 32, 0
	v_ldexp_f32 v1, v1, s4
	v_log_f32_e32 v1, v1
	v_cndmask_b32_e32 v2, 0, v232, vcc
	s_mov_b32 s4, 0xc2fc0000
	v_cvt_f32_ubyte0_e32 v3, s6
	v_sub_f32_e32 v1, v1, v2
	v_floor_f32_e32 v1, v1
	v_cmp_gt_f32_e32 vcc, s4, v1
	s_and_b64 s[4:5], vcc, exec
	s_cselect_b32 s4, 0xffffffc0, 0
	v_cndmask_b32_e32 v2, 0, v233, vcc
	v_add_f32_e32 v1, v1, v2
	v_exp_f32_e32 v1, v1
	v_rcp_iflag_f32_e32 v4, v3
	v_ldexp_f32 v1, v1, s4
	s_sext_i32_i8 s4, s3
	v_cvt_f32_i32_e32 v2, s4
	s_ashr_i32 s5, s4, 30
	s_or_b32 s7, s5, 1
	v_mul_f32_e32 v4, v2, v4
	v_trunc_f32_e32 v4, v4
	v_fma_f32 v2, -v4, v3, v2
	v_cvt_i32_f32_e32 v4, v4
	v_cmp_ge_f32_e64 s[4:5], |v2|, v3
	s_and_b64 s[4:5], s[4:5], exec
	s_cselect_b32 s4, s7, 0
	v_readfirstlane_b32 s5, v4
	s_add_i32 s4, s5, s4
	s_sext_i32_i8 s5, s4
	s_mul_i32 s4, s4, s6
	s_lshl_b32 s28, s5, 8
	s_sub_i32 s3, s3, s4
	s_sext_i32_i8 s3, s3
	v_add_u32_e32 v2, s28, v143
	s_lshl_b32 s36, s3, 7
	v_mad_i64_i32 v[2:3], s[4:5], s26, v2, 0
	v_lshl_add_u64 v[2:3], v[2:3], 2, s[52:53]
	s_ashr_i32 s37, s36, 31
	v_lshl_add_u64 v[2:3], s[36:37], 2, v[2:3]
	v_lshl_add_u64 v[10:11], v[2:3], 0, v[198:199]
	s_lshl_b32 s34, s26, 2
	v_lshl_add_u64 v[14:15], v[10:11], 0, s[34:35]
	v_lshl_add_u64 v[18:19], v[14:15], 0, s[34:35]
	v_lshl_add_u64 v[22:23], v[18:19], 0, s[34:35]
	v_lshl_add_u64 v[26:27], v[22:23], 0, s[34:35]
	v_lshl_add_u64 v[30:31], v[26:27], 0, s[34:35]
	v_lshl_add_u64 v[34:35], v[30:31], 0, s[34:35]
	v_lshl_add_u64 v[38:39], v[34:35], 0, s[34:35]
	v_lshl_add_u64 v[42:43], v[38:39], 0, s[34:35]
	v_lshl_add_u64 v[46:47], v[42:43], 0, s[34:35]
	v_lshl_add_u64 v[50:51], v[46:47], 0, s[34:35]
	v_lshl_add_u64 v[54:55], v[50:51], 0, s[34:35]
	v_lshl_add_u64 v[58:59], v[54:55], 0, s[34:35]
	v_lshl_add_u64 v[62:63], v[58:59], 0, s[34:35]
	v_lshl_add_u64 v[66:67], v[62:63], 0, s[34:35]
	global_load_dwordx4 v[2:5], v[10:11], off nt
	s_nop 0
	global_load_dwordx4 v[10:13], v[14:15], off nt
	s_nop 0
	global_load_dwordx4 v[14:17], v[18:19], off nt
	s_nop 0
	global_load_dwordx4 v[18:21], v[22:23], off nt
	s_nop 0
	global_load_dwordx4 v[22:25], v[26:27], off nt
	s_nop 0
	global_load_dwordx4 v[26:29], v[30:31], off nt
	s_nop 0
	global_load_dwordx4 v[30:33], v[34:35], off nt
	s_nop 0
	global_load_dwordx4 v[34:37], v[38:39], off nt
	s_nop 0
	global_load_dwordx4 v[38:41], v[42:43], off nt
	s_nop 0
	global_load_dwordx4 v[42:45], v[46:47], off nt
	s_nop 0
	global_load_dwordx4 v[46:49], v[50:51], off nt
	s_nop 0
	global_load_dwordx4 v[50:53], v[54:55], off nt
	s_nop 0
	global_load_dwordx4 v[54:57], v[58:59], off nt
	s_nop 0
	global_load_dwordx4 v[58:61], v[62:63], off nt
	s_nop 0
	global_load_dwordx4 v[62:65], v[66:67], off nt
	v_lshl_add_u64 v[66:67], v[66:67], 0, s[34:35]
	global_load_dwordx4 v[66:69], v[66:67], off nt
	s_waitcnt vmcnt(20)
	s_branch .Lcvw_3

; #define LAS __attribute__((address_space(3)))
; __device__ __forceinline__ int map_row_rt(int map, int n) { return map == 0 ? n : (map == 1 ? map_row<1>(n) : (map == 3 ? map_row<3>(n) : map_row<2>(n))); }
; __device__ __forceinline__ void witem_store(const Frame& F, const WItem& t, const f32x4 (&v)[16], LAS unsigned char* tile) {
;     const int i = F.lane & 31, hi = F.lane >> 5;
; #pragma unroll
;     for (int j = 0; j < 4; ++j) {
;         u32x4 o;
; #pragma unroll
;         for (int d = 0; d < 4; ++d) { int r = __builtin_amdgcn_cvt_pk_fp8_f32(v[4 * d][j] * t.scale, v[4 * d + 1][j] * t.scale, 0, false);
;             r = __builtin_amdgcn_cvt_pk_fp8_f32(v[4 * d + 2][j] * t.scale, v[4 * d + 3][j] * t.scale, r, true); o[d] = (unsigned)r; }
;         *(LAS u32x4*)(tile + (32 * j + i) * 272 + 32 * F.wave + 16 * hi) = o;
;     }
;     __syncthreads();
;     const int c = F.tid & 15;
; #pragma unroll
;     for (int pass = 0; pass < 4; ++pass) { const int n = (F.tid >> 4) + 32 * pass, rho = (n & 3) * 32 + (n >> 2);
;         const u32x4 o = *(const LAS u32x4*)(tile + rho * 272 + 16 * c);
;         *(u32x4*)(t.WT + (size_t)map_row_rt(t.map, t.n0 + n) * D + t.k0 + 16 * c) = o; }
; __device__ __forceinline__ void fp8_convert_range(const Frame& F, int l, int start, int stride, int limit) {
;     __syncthreads();
;     WItem ta, tb; f32x4 va[16], vb[16];
;     int it = start;
;     bool ha = it < limit && witem_decode(F, l, it, ta);
;     if (ha) witem_load(ta, F.wave, F.lane, va);
.LBB0_1859:
	v_readlane_b32 s4, v248, 1
	v_readlane_b32 s5, v248, 2
	s_movk_i32 s10, 0xc00
	s_and_b64 vcc, exec, s[4:5]
	s_cbranch_vccnz .LBB0_1998
	v_readlane_b32 s3, v248, 0
	v_ashrrev_i32_e32 v137, 4, v0
	s_lshl_b32 s3, s3, 5
	s_waitcnt vmcnt(0)
	v_lshlrev_b32_e32 v8, 5, v137
	v_add_u32_e32 v140, 32, v137
	v_add_u32_e32 v141, 64, v137
	v_add_u32_e32 v142, 0x60, v137
	s_add_i32 s4, s3, 0
	v_and_b32_e32 v8, 0x60, v8
	v_ashrrev_i32_e32 v9, 6, v0
	s_waitcnt vmcnt(8)
	v_lshrrev_b32_e32 v70, 2, v140
	v_lshrrev_b32_e32 v71, 2, v141
	v_lshrrev_b32_e32 v72, 2, v142
	v_and_b32_e32 v6, 31, v0
	v_mov_b32_e32 v7, s4
	s_movk_i32 s4, 0x110
	v_add_u32_e32 v9, v8, v9
	v_add_u32_e32 v70, v8, v70
	v_add_u32_e32 v71, v8, v71
	v_add_u32_e32 v8, v8, v72
	v_mad_u32_u24 v6, v6, s4, v7
	v_mul_lo_u32 v9, v9, s4
	v_mul_lo_u32 v70, v70, s4
	v_mul_lo_u32 v71, v71, s4
	v_mul_lo_u32 v8, v8, s4
	v_readlane_b32 s4, v248, 3
	v_readlane_b32 s5, v248, 4
	s_lshl_b64 s[4:5], s[4:5], 2
	s_add_u32 s4, s78, s4
	s_addc_u32 s5, s79, s5
	s_add_u32 s36, s4, 0x2000
	s_addc_u32 s37, s5, 0
	s_add_u32 s9, s78, 0x58000000
	s_addc_u32 s11, s79, 0
	v_lshlrev_b32_e32 v7, 4, v0
	s_add_u32 s40, s4, 0x2004
	v_and_b32_e32 v134, 0xf0, v7
	v_lshrrev_b32_e32 v72, 1, v0
	s_addc_u32 s41, s5, 0
	v_add_u32_e32 v7, 0, v134
	v_and_b32_e32 v72, 16, v72
	s_add_u32 s52, s78, 0x38000000
	v_lshlrev_b32_e32 v73, 2, v159
	v_mov_b32_e32 v135, v199
	s_addc_u32 s53, s79, 0
	v_or_b32_e32 v143, s3, v72
	v_and_b32_e32 v136, 0x7c, v73
	v_add_u32_e32 v144, v6, v72
	v_add_u32_e32 v145, v7, v9
	v_add_u32_e32 v146, v7, v70
	v_add_u32_e32 v147, v7, v71
	v_add_u32_e32 v148, v7, v8
	v_readlane_b32 s54, v250, 49
	s_mov_b32 s101, 0
	s_branch .LBB0_1863

; __device__ __forceinline__ float w_qscale(float wmax) { return exp2f(floorf(log2f(128.f / fmaxf(wmax, 1e-30f)))); }
; __device__ __forceinline__ bool witem_decode(const Frame& F, int l, int it, WItem& t) {
;     constexpr int I_GU = 4 * 16, I_DN = 4 * 8, N_GU = NE * I_GU, N_DN = NE * I_DN;
;     const float* wmax = (const float*)((const unsigned*)(F.ws + WS_CTL) + CW_WMAX);
;     int r = it, nblk, item;
;     if (r < N_GU) { const int le = l * NE + r / I_GU; t.W = F.in[16] + (size_t)le * D * 2048; t.WT = (unsigned char*)(F.ws + WS_WGU) + (size_t)le * 2048 * D; t.N = 2048; t.map = 1; nblk = 16; item = r % I_GU; t.scale = w_qscale(wmax[l * 2 + 0]); }
;     else if ((r -= N_GU) < N_DN) { const int le = l * NE + r / I_DN; t.W = F.in[18] + (size_t)le * FF * D; t.WT = (unsigned char*)(F.ws + WS_WDN) + (size_t)le * D * FF; t.N = D; t.map = 3; nblk = 8; item = r % I_DN; t.scale = w_qscale(wmax[l * 2 + 1]); }
;     else return false;
;     t.k0 = 256 * (item / nblk); t.n0 = 128 * (item % nblk); return true;
; }
; __device__ __forceinline__ void witem_load(const WItem& t, int wave, int lane, f32x4 (&v)[16]) {
;     const float* wp = t.W + (size_t)(t.k0 + 32 * wave + 16 * (lane >> 5)) * t.N + t.n0 + 4 * (lane & 31);
; #pragma unroll
;     for (int q = 0; q < 16; ++q) v[q] = __builtin_nontemporal_load((const f32x4*)(wp + (size_t)q * t.N));
; }
; __device__ __forceinline__ void fp8_convert_range(const Frame& F, int l, int start, int stride, int limit) {
;     ...
;     while (ha) {
;         const bool hb = it + stride < limit && witem_decode(F, l, it + stride, tb);
;         if (hb) witem_load(tb, F.wave, F.lane, vb);
;         witem_store(F, ta, va, F.lds);
;         if (!hb) break;
;         it += 2 * stride;
;         ha = it < limit && witem_decode(F, l, it, ta);
;         if (ha) witem_load(ta, F.wave, F.lane, va);
;         witem_store(F, tb, vb, F.lds + 34816);
.LBB0_1938:
	s_load_dword s100, s[4:5], 0x0
	s_mov_b32 s7, 0x43000000
	v_lshlrev_b32_e32 v198, 2, v136
	s_movk_i32 s10, 0xc00
	s_waitcnt lgkmcnt(0)
	v_mov_b32_e32 v1, s100
	v_max_f32_e32 v1, v1, v1
	v_max_f32_e32 v1, 0xda24260, v1
	v_div_scale_f32 v2, s[4:5], v1, v1, s7
	v_rcp_f32_e32 v3, v2
	s_mov_b32 s4, 0x800000
	v_fma_f32 v4, -v2, v3, 1.0
	v_fmac_f32_e32 v3, v4, v3
	v_div_scale_f32 v4, vcc, s7, v1, s7
	v_mul_f32_e32 v5, v4, v3
	v_fma_f32 v10, -v2, v5, v4
	v_fmac_f32_e32 v5, v10, v3
	v_fma_f32 v2, -v2, v5, v4
	v_div_fmas_f32 v2, v2, v3, v5
	v_div_fixup_f32 v1, v2, v1, s7
	v_cmp_gt_f32_e32 vcc, s4, v1
	s_and_b64 s[4:5], vcc, exec
	s_cselect_b32 s4, 32, 0
	v_ldexp_f32 v1, v1, s4
	v_log_f32_e32 v1, v1
	v_cndmask_b32_e32 v2, 0, v232, vcc
	s_mov_b32 s4, 0xc2fc0000
	v_cvt_f32_ubyte0_e32 v3, s6
	v_sub_f32_e32 v1, v1, v2
	v_floor_f32_e32 v1, v1
	v_cmp_gt_f32_e32 vcc, s4, v1
	s_and_b64 s[4:5], vcc, exec
	s_cselect_b32 s4, 0xffffffc0, 0
	v_cndmask_b32_e32 v2, 0, v233, vcc
	v_add_f32_e32 v1, v1, v2
	v_exp_f32_e32 v1, v1
	v_rcp_iflag_f32_e32 v4, v3
	v_ldexp_f32 v1, v1, s4
	s_sext_i32_i8 s4, s3
	v_cvt_f32_i32_e32 v2, s4
	s_ashr_i32 s5, s4, 30
	s_or_b32 s7, s5, 1
	v_mul_f32_e32 v4, v2, v4
	v_trunc_f32_e32 v4, v4
	v_fma_f32 v2, -v4, v3, v2
	v_cvt_i32_f32_e32 v4, v4
	v_cmp_ge_f32_e64 s[4:5], |v2|, v3
	s_and_b64 s[4:5], s[4:5], exec
	s_cselect_b32 s4, s7, 0
	v_readfirstlane_b32 s5, v4
	s_add_i32 s4, s5, s4
	s_sext_i32_i8 s5, s4
	s_mul_i32 s4, s4, s6
	s_lshl_b32 s14, s5, 8
	s_sub_i32 s3, s3, s4
	s_sext_i32_i8 s3, s3
	v_add_u32_e32 v2, s14, v143
	s_lshl_b32 s28, s3, 7
	v_mad_i64_i32 v[2:3], s[4:5], s26, v2, 0
	v_lshl_add_u64 v[2:3], v[2:3], 2, s[50:51]
	s_ashr_i32 s29, s28, 31
	v_lshl_add_u64 v[2:3], s[28:29], 2, v[2:3]
	v_lshl_add_u64 v[10:11], v[2:3], 0, v[198:199]
	s_lshl_b32 s34, s26, 2
	v_lshl_add_u64 v[14:15], v[10:11], 0, s[34:35]
	v_lshl_add_u64 v[18:19], v[14:15], 0, s[34:35]
	v_lshl_add_u64 v[22:23], v[18:19], 0, s[34:35]
	v_lshl_add_u64 v[26:27], v[22:23], 0, s[34:35]
	v_lshl_add_u64 v[30:31], v[26:27], 0, s[34:35]
	v_lshl_add_u64 v[34:35], v[30:31], 0, s[34:35]
	v_lshl_add_u64 v[38:39], v[34:35], 0, s[34:35]
	v_lshl_add_u64 v[42:43], v[38:39], 0, s[34:35]
	v_lshl_add_u64 v[46:47], v[42:43], 0, s[34:35]
	v_lshl_add_u64 v[50:51], v[46:47], 0, s[34:35]
	v_lshl_add_u64 v[54:55], v[50:51], 0, s[34:35]
	v_lshl_add_u64 v[58:59], v[54:55], 0, s[34:35]
	v_lshl_add_u64 v[62:63], v[58:59], 0, s[34:35]
	v_lshl_add_u64 v[66:67], v[62:63], 0, s[34:35]
	global_load_dwordx4 v[2:5], v[10:11], off nt
	s_nop 0
	global_load_dwordx4 v[10:13], v[14:15], off nt
	s_nop 0
	global_load_dwordx4 v[14:17], v[18:19], off nt
	s_nop 0
	global_load_dwordx4 v[18:21], v[22:23], off nt
	s_nop 0
	global_load_dwordx4 v[22:25], v[26:27], off nt
	s_nop 0
	global_load_dwordx4 v[26:29], v[30:31], off nt
	s_nop 0
	global_load_dwordx4 v[30:33], v[34:35], off nt
	s_nop 0
	global_load_dwordx4 v[34:37], v[38:39], off nt
	s_nop 0
	global_load_dwordx4 v[38:41], v[42:43], off nt
	s_nop 0
	global_load_dwordx4 v[42:45], v[46:47], off nt
	s_nop 0
	global_load_dwordx4 v[46:49], v[50:51], off nt
	s_nop 0
	global_load_dwordx4 v[50:53], v[54:55], off nt
	s_nop 0
	global_load_dwordx4 v[54:57], v[58:59], off nt
	s_nop 0
	global_load_dwordx4 v[58:61], v[62:63], off nt
	s_nop 0
	global_load_dwordx4 v[62:65], v[66:67], off nt
	v_lshl_add_u64 v[66:67], v[66:67], 0, s[34:35]
	global_load_dwordx4 v[66:69], v[66:67], off nt
	s_waitcnt vmcnt(20)
	s_branch .Lcvw_5
